# barrier-shadow weight prefetch: exit s_barrier of the grid barrier moved below the first tile's address math + 4 weight K-tile-0 DMAs (G3a,G4,G5,G6)
# baseline (speedup 1.0000x reference)
; #define PG8_STAGE(bufoff, gbase, voff) do { _Pragma("unroll") for (int _i = 0; _i < 2; ++_i) \
;         __builtin_amdgcn_global_load_lds((const unsigned*)((const char*)(gbase) + (voff)[_i]), (PG8_LAS unsigned*)(lds + (bufoff) + ldsw + _i * 8192), 16, 0, 0); } while (0)
; #define PG8_WAIT_V(n) asm volatile("s_waitcnt vmcnt(" #n ")" ::: "memory")
; template <class Epi, class Sched, bool ALIGN_EPI = false, bool SP2 = false>
; __device__ __forceinline__ void gemm_phase(PG8_LAS unsigned char* lds, const Gemm g, const Sched& S, const Epi& E) {
;     ...
;     for (int i = 0; i < 2; ++i) { int R, C; stage_rc(tid * 16 + i * 8192, R, C); const int Rb = Epi::PERM ? ((R & ~31) + perm32(R & 31)) : R;
;         voffA[i] = (unsigned)(R * K + C) * 2u; voffB[i] = (unsigned)(Rb * K + C) * 2u; }
;     const size_t kstep = (size_t)(BK * 2);
;     const size_t hstep = (size_t)HALF * K * 2;
;     const size_t tstep = 2 * hstep;
;     const unsigned ldsw = (unsigned)wid * 1024u;
;     const int aoff = lds_byte(wr * 64 + fr, fq * 8), boff = lds_byte(wc * 32 + fr, fq * 8);
;     ...
;     Unit cur, nxt; int ui = 0;
;     if (!S.next(0, cur)) return;
;     f32x4 acc[2][2][4][2];
; #pragma unroll
;     for (int a = 0; a < 2; ++a)
; #pragma unroll
;         for (int b = 0; b < 2; ++b)
; #pragma unroll
;             for (int m = 0; m < 4; ++m)
; #pragma unroll
;                 for (int n = 0; n < 2; ++n) acc[a][b][m][n] = (f32x4){0.f, 0.f, 0.f, 0.f};
;     bf16x8 At[4][2], B0[2][2], B1[2][2];
;     const char* cA = (const char*)g.A + (size_t)cur.pm * tstep; const char* cB = (const char*)g.Bt + (size_t)cur.pn * tstep;
;     S.a_ready(cur);
;     if constexpr (SP2) {
;         PG8_STAGE(PG8_SB(0, 0), cB, voffB); PG8_STAGE(PG8_SB(0, 1), cB + hstep, voffB); PG8_STAGE(PG8_SA(0, 0), cA, voffA); PG8_STAGE(PG8_SA(0, 1), cA + hstep, voffA);
;         if (wr == 1) PG8_BAR;
;         PG8_WAIT_V(2); PG8_BAR;
;         PG8_STAGE(PG8_SB(1, 0), cB + kstep, voffB); PG8_STAGE(PG8_SA(1, 0), cA + kstep, voffA); PG8_STAGE(PG8_SB(1, 1), cB + hstep + kstep, voffB);
;         PG8_WAIT_V(6); PG8_BAR;
; __global__ void __launch_bounds__(512, 2) mk_fwd(Args a) {
;     ...
;         { pg8::Gemm g{attn, Wl + W_AO, NTOK_P, DM, 512}; pg8::StaticOrder S; S.init(NTOK_P, DM, G, bx); EpiMix<false> E{Z + ZG, mixed};
;           pg8::gemm_phase<EpiMix<false>, pg8::StaticOrder, true, true>(lds, g, S, E);
.LBB0_663:
	s_or_b64 exec, exec, s[0:1]
	v_readlane_b32 s0, v255, 37
	s_add_u32 s26, s0, 0x700000
	v_readlane_b32 s0, v255, 38
	s_addc_u32 s54, s0, 0
	v_readlane_b32 s0, v255, 39
	v_mov_b32_e32 v21, v184
	v_readlane_b32 s1, v255, 40
	s_waitcnt lgkmcnt(0)
	s_and_b64 vcc, exec, s[0:1]
	v_readfirstlane_b32 s6, v21
	s_cbranch_vccz .Lbsh_g3a_go
	s_barrier
	s_branch .LBB0_683
.Lbsh_g3a_go:
	v_lshlrev_b32_e32 v0, 4, v21
	v_add_u32_e32 v2, 0x2000, v0
	v_ashrrev_i32_e32 v3, 31, v2
	v_lshrrev_b32_e32 v3, 22, v3
	v_add_u32_e32 v3, v2, v3
	v_ashrrev_i32_e32 v20, 10, v3
	v_mul_i32_i24_e32 v3, 0x400, v20
	v_sub_u32_e32 v2, v2, v3
	v_lshrrev_b32_e32 v3, 4, v2
	v_bitop3_b32 v2, v3, v2, 32 bitop3:0x6c
	v_ashrrev_i32_e32 v3, 31, v2
	v_lshrrev_b32_e32 v3, 26, v3
	v_add_u32_e32 v3, v2, v3
	v_lshlrev_b32_e32 v23, 3, v20
	v_ashrrev_i32_e32 v22, 6, v3
	v_and_b32_e32 v23, -16, v23
	v_add_u32_e32 v24, v22, v23
	v_and_b32_e32 v23, 3, v22
	s_mov_b32 s0, 0x3fffe0
	v_lshrrev_b32_e32 v25, 2, v24
	v_lshlrev_b32_e32 v26, 1, v24
	v_and_b32_e32 v3, 0xc0, v3
	v_and_or_b32 v23, v24, s0, v23
	v_and_b32_e32 v25, 4, v25
	v_and_b32_e32 v26, 24, v26
	v_sub_u32_e32 v2, v2, v3
	v_mov_b32_e32 v30, 1
	v_or3_b32 v25, v23, v25, v26
	v_lshlrev_b32_e32 v23, 5, v20
	v_ashrrev_i16_sdwa v2, v30, sext(v2) dst_sel:DWORD dst_unused:UNUSED_PAD src0_sel:DWORD src1_sel:BYTE_0
	v_and_b32_e32 v26, 32, v23
	v_bfe_i32 v23, v2, 0, 16
	v_add_lshl_u32 v3, v26, v23, 1
	v_lshl_add_u32 v2, v25, 10, v3
	v_lshl_add_u32 v148, v24, 10, v3
	v_bfe_i32 v3, v21, 27, 1
	v_lshrrev_b32_e32 v3, 22, v3
	v_add_u32_e32 v3, v0, v3
	v_and_b32_e32 v3, 0xfffffc00, v3
	v_sub_u32_e32 v0, v0, v3
	v_lshrrev_b32_e32 v3, 4, v0
	v_ashrrev_i32_e32 v25, 31, v21
	v_bitop3_b32 v0, v3, v0, 32 bitop3:0x6c
	v_lshrrev_b32_e32 v25, 26, v25
	v_ashrrev_i32_e32 v3, 31, v0
	v_add_u32_e32 v25, v21, v25
	v_lshrrev_b32_e32 v3, 26, v3
	v_ashrrev_i32_e32 v25, 6, v25
	v_add_u32_e32 v3, v0, v3
	v_lshlrev_b32_e32 v26, 3, v25
	v_ashrrev_i32_e32 v24, 6, v3
	v_and_b32_e32 v26, -16, v26
	v_add_u32_e32 v27, v24, v26
	v_and_b32_e32 v26, 3, v24
	v_lshrrev_b32_e32 v28, 2, v27
	v_lshlrev_b32_e32 v29, 1, v27
	v_and_b32_e32 v3, 0xc0, v3
	s_ashr_i32 s8, s6, 6
	v_and_or_b32 v26, v27, s0, v26
	v_and_b32_e32 v28, 4, v28
	v_and_b32_e32 v29, 24, v29
	v_sub_u32_e32 v0, v0, v3
	s_ashr_i32 s7, s6, 8
	s_lshl_b32 s55, s8, 10
	v_or3_b32 v28, v26, v28, v29
	v_lshlrev_b32_e32 v26, 5, v25
	v_ashrrev_i16_sdwa v0, v30, sext(v0) dst_sel:DWORD dst_unused:UNUSED_PAD src0_sel:DWORD src1_sel:BYTE_0
	v_readlane_b32 s0, v254, 14
	v_and_b32_e32 v29, 32, v26
	v_bfe_i32 v26, v0, 0, 16
	v_readlane_b32 s1, v254, 15
	s_add_u32 s0, s26, s0
	v_add_lshl_u32 v3, v29, v26, 1
	s_addc_u32 s1, s54, s1
	s_add_i32 s56, s55, 0
	v_lshl_add_u32 v0, v28, 10, v3
	s_add_i32 m0, s56, 0x10000
	v_lshl_add_u32 v150, v27, 10, v3
	global_load_lds_dwordx4 v0, s[0:1]
	s_add_i32 m0, s56, 0x12000
	s_add_u32 s4, s0, 0x20000
	global_load_lds_dwordx4 v2, s[0:1]
	s_addc_u32 s5, s1, 0
	s_add_i32 m0, s56, 0x14000
	s_add_i32 s57, s56, 0x2000
	global_load_lds_dwordx4 v0, s[4:5]
	s_add_i32 m0, s56, 0x16000
	s_add_i32 s58, s56, 0x4000
	global_load_lds_dwordx4 v2, s[4:5]
	v_readlane_b32 s4, v254, 16
	s_barrier
	s_mov_b32 m0, s56
	v_readlane_b32 s5, v254, 17
	s_add_i32 s59, s56, 0x6000
	s_cmp_eq_u32 s7, 1
	s_nop 2
	global_load_lds_dwordx4 v150, s[4:5]
	s_mov_b32 m0, s57
	s_nop 0
	global_load_lds_dwordx4 v148, s[4:5]
	v_readlane_b32 s4, v254, 18
	s_mov_b32 m0, s58
	v_readlane_b32 s5, v254, 19
	s_nop 4
	global_load_lds_dwordx4 v150, s[4:5]
	s_mov_b32 m0, s59
	s_nop 0
	global_load_lds_dwordx4 v148, s[4:5]
	s_cselect_b64 s[4:5], -1, 0
	s_cmp_lg_u32 s7, 1
	s_cbranch_scc1 .LBB0_666
	s_barrier

; #define PG8_STAGE(bufoff, gbase, voff) do { _Pragma("unroll") for (int _i = 0; _i < 2; ++_i) \
;         __builtin_amdgcn_global_load_lds((const unsigned*)((const char*)(gbase) + (voff)[_i]), (PG8_LAS unsigned*)(lds + (bufoff) + ldsw + _i * 8192), 16, 0, 0); } while (0)
; #define PG8_WAIT_V(n) asm volatile("s_waitcnt vmcnt(" #n ")" ::: "memory")
; template <class Epi, class Sched, bool ALIGN_EPI = false, bool SP2 = false>
; __device__ __forceinline__ void gemm_phase(PG8_LAS unsigned char* lds, const Gemm g, const Sched& S, const Epi& E) {
;     ...
;     for (int i = 0; i < 2; ++i) { int R, C; stage_rc(tid * 16 + i * 8192, R, C); const int Rb = Epi::PERM ? ((R & ~31) + perm32(R & 31)) : R;
;         voffA[i] = (unsigned)(R * K + C) * 2u; voffB[i] = (unsigned)(Rb * K + C) * 2u; }
;     const size_t kstep = (size_t)(BK * 2);
;     const size_t hstep = (size_t)HALF * K * 2;
;     const size_t tstep = 2 * hstep;
;     const unsigned ldsw = (unsigned)wid * 1024u;
;     const int aoff = lds_byte(wr * 64 + fr, fq * 8), boff = lds_byte(wc * 32 + fr, fq * 8);
;     ...
;     Unit cur, nxt; int ui = 0;
;     if (!S.next(0, cur)) return;
;     f32x4 acc[2][2][4][2];
; #pragma unroll
;     for (int a = 0; a < 2; ++a)
; #pragma unroll
;         for (int b = 0; b < 2; ++b)
; #pragma unroll
;             for (int m = 0; m < 4; ++m)
; #pragma unroll
;                 for (int n = 0; n < 2; ++n) acc[a][b][m][n] = (f32x4){0.f, 0.f, 0.f, 0.f};
;     bf16x8 At[4][2], B0[2][2], B1[2][2];
;     const char* cA = (const char*)g.A + (size_t)cur.pm * tstep; const char* cB = (const char*)g.Bt + (size_t)cur.pn * tstep;
;     S.a_ready(cur);
;     if constexpr (SP2) {
;         PG8_STAGE(PG8_SB(0, 0), cB, voffB); PG8_STAGE(PG8_SB(0, 1), cB + hstep, voffB); PG8_STAGE(PG8_SA(0, 0), cA, voffA); PG8_STAGE(PG8_SA(0, 1), cA + hstep, voffA);
;         if (wr == 1) PG8_BAR;
;         PG8_WAIT_V(2); PG8_BAR;
;         PG8_STAGE(PG8_SB(1, 0), cB + kstep, voffB); PG8_STAGE(PG8_SA(1, 0), cA + kstep, voffA); PG8_STAGE(PG8_SB(1, 1), cB + hstep + kstep, voffB);
;         PG8_WAIT_V(6); PG8_BAR;
; __global__ void __launch_bounds__(512, 2) mk_fwd(Args a) {
;     ...
;         { pg8::Gemm g{mixed, Wl + W_OUT, NTOK_P, DM, DM}; pg8::StaticOrder S; S.init(NTOK_P, DM, G, bx);
;           EpiRes E{bufA, xb2, nullptr, ss2};
;           pg8::gemm_phase<EpiRes, pg8::StaticOrder, true, true>(lds, g, S, E);
.LBB0_761:
	s_or_b64 exec, exec, s[0:1]
	s_add_u32 s4, s38, 0x10800
	s_addc_u32 s5, s39, 0
	v_readlane_b32 s0, v255, 37
	s_add_u32 s26, s0, 0x900000
	v_readlane_b32 s0, v255, 38
	s_addc_u32 s58, s0, 0
	v_readlane_b32 s0, v255, 39
	v_mov_b32_e32 v25, v184
	v_readlane_b32 s1, v255, 40
	s_waitcnt lgkmcnt(0)
	s_and_b64 vcc, exec, s[0:1]
	v_readfirstlane_b32 s8, v25
	s_cbranch_vccz .Lbsh_g4_go
	s_barrier
	s_branch .LBB0_797
.Lbsh_g4_go:
	v_lshlrev_b32_e32 v0, 4, v25
	v_add_u32_e32 v2, 0x2000, v0
	v_ashrrev_i32_e32 v3, 31, v2
	v_lshrrev_b32_e32 v3, 22, v3
	v_add_u32_e32 v3, v2, v3
	v_ashrrev_i32_e32 v24, 10, v3
	v_mul_i32_i24_e32 v3, 0x400, v24
	v_sub_u32_e32 v2, v2, v3
	v_lshrrev_b32_e32 v3, 4, v2
	v_bitop3_b32 v2, v3, v2, 32 bitop3:0x6c
	v_ashrrev_i32_e32 v3, 31, v2
	v_lshrrev_b32_e32 v3, 26, v3
	v_add_u32_e32 v3, v2, v3
	v_lshlrev_b32_e32 v20, 3, v24
	v_ashrrev_i32_e32 v26, 6, v3
	v_and_b32_e32 v20, -16, v20
	v_add_u32_e32 v20, v26, v20
	v_and_b32_e32 v21, 3, v26
	s_mov_b32 s0, 0x1fffe0
	v_lshrrev_b32_e32 v22, 2, v20
	v_lshlrev_b32_e32 v23, 1, v20
	v_and_b32_e32 v3, 0xc0, v3
	v_and_or_b32 v21, v20, s0, v21
	v_and_b32_e32 v22, 4, v22
	v_and_b32_e32 v23, 24, v23
	v_sub_u32_e32 v2, v2, v3
	v_mov_b32_e32 v30, 1
	v_or3_b32 v21, v21, v22, v23
	v_lshlrev_b32_e32 v22, 5, v24
	v_ashrrev_i16_sdwa v2, v30, sext(v2) dst_sel:DWORD dst_unused:UNUSED_PAD src0_sel:DWORD src1_sel:BYTE_0
	v_and_b32_e32 v22, 32, v22
	v_bfe_i32 v27, v2, 0, 16
	v_add_lshl_u32 v3, v22, v27, 1
	v_lshl_add_u32 v2, v21, 11, v3
	v_lshl_add_u32 v172, v20, 11, v3
	v_bfe_i32 v3, v25, 27, 1
	v_lshrrev_b32_e32 v3, 22, v3
	v_add_u32_e32 v3, v0, v3
	v_and_b32_e32 v3, 0xfffffc00, v3
	v_sub_u32_e32 v0, v0, v3
	v_lshrrev_b32_e32 v3, 4, v0
	v_ashrrev_i32_e32 v20, 31, v25
	v_bitop3_b32 v0, v3, v0, 32 bitop3:0x6c
	v_lshrrev_b32_e32 v20, 26, v20
	v_ashrrev_i32_e32 v3, 31, v0
	v_add_u32_e32 v20, v25, v20
	v_lshrrev_b32_e32 v3, 26, v3
	v_ashrrev_i32_e32 v29, 6, v20
	v_add_u32_e32 v3, v0, v3
	v_lshlrev_b32_e32 v20, 3, v29
	v_ashrrev_i32_e32 v28, 6, v3
	v_and_b32_e32 v20, -16, v20
	v_add_u32_e32 v20, v28, v20
	v_and_b32_e32 v21, 3, v28
	v_lshrrev_b32_e32 v22, 2, v20
	v_lshlrev_b32_e32 v23, 1, v20
	v_and_b32_e32 v3, 0xc0, v3
	s_ashr_i32 s10, s8, 6
	v_and_or_b32 v21, v20, s0, v21
	v_and_b32_e32 v22, 4, v22
	v_and_b32_e32 v23, 24, v23
	v_sub_u32_e32 v0, v0, v3
	s_ashr_i32 s9, s8, 8
	s_lshl_b32 s59, s10, 10
	v_or3_b32 v21, v21, v22, v23
	v_lshlrev_b32_e32 v22, 5, v29
	v_ashrrev_i16_sdwa v0, v30, sext(v0) dst_sel:DWORD dst_unused:UNUSED_PAD src0_sel:DWORD src1_sel:BYTE_0
	v_readlane_b32 s0, v254, 41
	v_and_b32_e32 v22, 32, v22
	v_bfe_i32 v30, v0, 0, 16
	v_readlane_b32 s1, v254, 42
	s_add_u32 s0, s26, s0
	v_add_lshl_u32 v3, v22, v30, 1
	s_addc_u32 s1, s58, s1
	s_add_i32 s62, s59, 0
	v_lshl_add_u32 v0, v21, 11, v3
	s_add_i32 m0, s62, 0x10000
	v_lshl_add_u32 v174, v20, 11, v3
	global_load_lds_dwordx4 v0, s[0:1]
	s_add_i32 m0, s62, 0x12000
	s_add_u32 s6, s0, 0x40000
	global_load_lds_dwordx4 v2, s[0:1]
	s_addc_u32 s7, s1, 0
	s_add_i32 m0, s62, 0x14000
	s_add_i32 s63, s62, 0x2000
	global_load_lds_dwordx4 v0, s[6:7]
	s_add_i32 m0, s62, 0x16000
	s_add_i32 s66, s62, 0x4000
	global_load_lds_dwordx4 v2, s[6:7]
	v_readlane_b32 s6, v254, 43
	s_barrier
	s_mov_b32 m0, s62
	v_readlane_b32 s7, v254, 44
	s_add_i32 s67, s62, 0x6000
	v_mov_b32_e32 v3, v1
	s_cmp_eq_u32 s9, 1
	v_lshl_add_u64 v[20:21], s[0:1], 0, v[0:1]
	v_lshl_add_u64 v[22:23], s[0:1], 0, v[2:3]
	global_load_lds_dwordx4 v174, s[6:7]
	s_mov_b32 m0, s63
	s_nop 0
	global_load_lds_dwordx4 v172, s[6:7]
	v_readlane_b32 s6, v254, 45
	s_mov_b32 m0, s66
	v_readlane_b32 s7, v254, 46
	s_nop 4
	global_load_lds_dwordx4 v174, s[6:7]
	s_mov_b32 m0, s67
	s_nop 0
	global_load_lds_dwordx4 v172, s[6:7]
	s_cselect_b64 s[6:7], -1, 0
	s_cmp_lg_u32 s9, 1
	s_cbranch_scc1 .LBB0_764
	s_barrier

; #define PG8_STAGE(bufoff, gbase, voff) do { _Pragma("unroll") for (int _i = 0; _i < 2; ++_i) \
;         __builtin_amdgcn_global_load_lds((const unsigned*)((const char*)(gbase) + (voff)[_i]), (PG8_LAS unsigned*)(lds + (bufoff) + ldsw + _i * 8192), 16, 0, 0); } while (0)
; #define PG8_WAIT_V(n) asm volatile("s_waitcnt vmcnt(" #n ")" ::: "memory")
; #define PG8_BAR __builtin_amdgcn_s_barrier()
; template <class Epi, class Sched, bool ALIGN_EPI = false, bool SP2 = false>
; __device__ __forceinline__ void gemm_phase(PG8_LAS unsigned char* lds, const Gemm g, const Sched& S, const Epi& E) {
;     ...
;     for (int i = 0; i < 2; ++i) { int R, C; stage_rc(tid * 16 + i * 8192, R, C); const int Rb = Epi::PERM ? ((R & ~31) + perm32(R & 31)) : R;
;         voffA[i] = (unsigned)(R * K + C) * 2u; voffB[i] = (unsigned)(Rb * K + C) * 2u; }
;     const size_t kstep = (size_t)(BK * 2);
;     const size_t hstep = (size_t)HALF * K * 2;
;     const size_t tstep = 2 * hstep;
;     const unsigned ldsw = (unsigned)wid * 1024u;
;     const int aoff = lds_byte(wr * 64 + fr, fq * 8), boff = lds_byte(wc * 32 + fr, fq * 8);
;     ...
;     Unit cur, nxt; int ui = 0;
;     if (!S.next(0, cur)) return;
;     f32x4 acc[2][2][4][2];
; #pragma unroll
;     for (int a = 0; a < 2; ++a)
; #pragma unroll
;         for (int b = 0; b < 2; ++b)
; #pragma unroll
;             for (int m = 0; m < 4; ++m)
; #pragma unroll
;                 for (int n = 0; n < 2; ++n) acc[a][b][m][n] = (f32x4){0.f, 0.f, 0.f, 0.f};
;     bf16x8 At[4][2], B0[2][2], B1[2][2];
;     const char* cA = (const char*)g.A + (size_t)cur.pm * tstep; const char* cB = (const char*)g.Bt + (size_t)cur.pn * tstep;
;     S.a_ready(cur);
;     if constexpr (SP2) {
;         PG8_STAGE(PG8_SB(0, 0), cB, voffB); PG8_STAGE(PG8_SB(0, 1), cB + hstep, voffB); PG8_STAGE(PG8_SA(0, 0), cA, voffA); PG8_STAGE(PG8_SA(0, 1), cA + hstep, voffA);
;         if (wr == 1) PG8_BAR;
;         PG8_WAIT_V(2); PG8_BAR;
;         PG8_STAGE(PG8_SB(1, 0), cB + kstep, voffB); PG8_STAGE(PG8_SA(1, 0), cA + kstep, voffA); PG8_STAGE(PG8_SB(1, 1), cB + hstep + kstep, voffB);
;         PG8_WAIT_V(6); PG8_BAR;
; __global__ void __launch_bounds__(512, 2) mk_fwd(Args a) {
;     ...
;         { pg8::Gemm g{xb2, Wl + W_UP, NTOK_P, FF, DM}; pg8::StaticOrder S; S.init(NTOK_P, FF, G, bx); EpiUp E{H, ss2};
;           pg8::gemm_phase<EpiUp, pg8::StaticOrder, true, true>(lds, g, S, E);
.LBB0_854:
	s_or_b64 exec, exec, s[0:1]
	v_readlane_b32 s0, v255, 37
	s_add_u32 s26, s0, 0xb00000
	v_readlane_b32 s0, v255, 38
	s_addc_u32 s56, s0, 0
	v_readlane_b32 s0, v253, 62
	v_mov_b32_e32 v20, v184
	v_readlane_b32 s1, v253, 63
	s_waitcnt lgkmcnt(0)
	s_andn2_b64 vcc, exec, s[0:1]
	v_readfirstlane_b32 s8, v20
	s_cbranch_vccz .Lbsh_g5_go
	s_barrier
	s_branch .LBB0_874
.Lbsh_g5_go:
	v_lshlrev_b32_e32 v0, 4, v20
	v_add_u32_e32 v2, 0x2000, v0
	v_ashrrev_i32_e32 v3, 31, v2
	v_lshrrev_b32_e32 v3, 22, v3
	v_add_u32_e32 v3, v2, v3
	v_ashrrev_i32_e32 v21, 10, v3
	v_mul_i32_i24_e32 v3, 0x400, v21
	v_sub_u32_e32 v2, v2, v3
	v_lshrrev_b32_e32 v3, 4, v2
	v_bitop3_b32 v2, v3, v2, 32 bitop3:0x6c
	v_ashrrev_i32_e32 v3, 31, v2
	v_lshrrev_b32_e32 v3, 26, v3
	v_add_u32_e32 v3, v2, v3
	v_lshlrev_b32_e32 v23, 3, v21
	v_ashrrev_i32_e32 v22, 6, v3
	v_and_b32_e32 v23, -16, v23
	v_add_u32_e32 v24, v22, v23
	v_and_b32_e32 v23, 3, v22
	s_mov_b32 s0, 0x1fffe0
	v_lshrrev_b32_e32 v25, 2, v24
	v_lshlrev_b32_e32 v26, 1, v24
	v_and_b32_e32 v3, 0xc0, v3
	v_and_or_b32 v23, v24, s0, v23
	v_and_b32_e32 v25, 4, v25
	v_and_b32_e32 v26, 24, v26
	v_sub_u32_e32 v2, v2, v3
	v_mov_b32_e32 v30, 1
	v_or3_b32 v25, v23, v25, v26
	v_lshlrev_b32_e32 v23, 5, v21
	v_ashrrev_i16_sdwa v2, v30, sext(v2) dst_sel:DWORD dst_unused:UNUSED_PAD src0_sel:DWORD src1_sel:BYTE_0
	v_and_b32_e32 v26, 32, v23
	v_bfe_i32 v23, v2, 0, 16
	v_add_lshl_u32 v3, v26, v23, 1
	v_lshl_add_u32 v2, v25, 11, v3
	v_lshl_add_u32 v148, v24, 11, v3
	v_bfe_i32 v3, v20, 27, 1
	v_lshrrev_b32_e32 v3, 22, v3
	v_add_u32_e32 v3, v0, v3
	v_and_b32_e32 v3, 0xfffffc00, v3
	v_sub_u32_e32 v0, v0, v3
	v_lshrrev_b32_e32 v3, 4, v0
	v_ashrrev_i32_e32 v25, 31, v20
	v_bitop3_b32 v0, v3, v0, 32 bitop3:0x6c
	v_lshrrev_b32_e32 v25, 26, v25
	v_ashrrev_i32_e32 v3, 31, v0
	v_add_u32_e32 v25, v20, v25
	v_lshrrev_b32_e32 v3, 26, v3
	v_ashrrev_i32_e32 v25, 6, v25
	v_add_u32_e32 v3, v0, v3
	v_lshlrev_b32_e32 v26, 3, v25
	v_ashrrev_i32_e32 v24, 6, v3
	v_and_b32_e32 v26, -16, v26
	v_add_u32_e32 v27, v24, v26
	v_and_b32_e32 v26, 3, v24
	v_lshrrev_b32_e32 v28, 2, v27
	v_lshlrev_b32_e32 v29, 1, v27
	v_and_b32_e32 v3, 0xc0, v3
	s_ashr_i32 s10, s8, 6
	v_and_or_b32 v26, v27, s0, v26
	v_and_b32_e32 v28, 4, v28
	v_and_b32_e32 v29, 24, v29
	v_sub_u32_e32 v0, v0, v3
	s_ashr_i32 s9, s8, 8
	s_lshl_b32 s57, s10, 10
	v_or3_b32 v28, v26, v28, v29
	v_lshlrev_b32_e32 v26, 5, v25
	v_ashrrev_i16_sdwa v0, v30, sext(v0) dst_sel:DWORD dst_unused:UNUSED_PAD src0_sel:DWORD src1_sel:BYTE_0
	v_readlane_b32 s0, v254, 25
	v_and_b32_e32 v29, 32, v26
	v_bfe_i32 v26, v0, 0, 16
	v_readlane_b32 s1, v254, 26
	s_add_u32 s0, s26, s0
	v_add_lshl_u32 v3, v29, v26, 1
	s_addc_u32 s1, s56, s1
	s_add_i32 s58, s57, 0
	v_lshl_add_u32 v0, v28, 11, v3
	s_add_i32 m0, s58, 0x10000
	v_lshl_add_u32 v150, v27, 11, v3
	global_load_lds_dwordx4 v0, s[0:1]
	s_add_i32 m0, s58, 0x12000
	s_add_u32 s6, s0, 0x40000
	global_load_lds_dwordx4 v2, s[0:1]
	s_addc_u32 s7, s1, 0
	s_add_i32 m0, s58, 0x14000
	s_add_i32 s59, s58, 0x2000
	global_load_lds_dwordx4 v0, s[6:7]
	s_add_i32 m0, s58, 0x16000
	s_add_i32 s62, s58, 0x4000
	global_load_lds_dwordx4 v2, s[6:7]
	v_readlane_b32 s6, v254, 29
	s_barrier
	s_mov_b32 m0, s58
	v_readlane_b32 s7, v254, 30
	s_add_i32 s63, s58, 0x6000
	s_cmp_eq_u32 s9, 1
	s_nop 2
	global_load_lds_dwordx4 v150, s[6:7]
	s_mov_b32 m0, s59
	s_nop 0
	global_load_lds_dwordx4 v148, s[6:7]
	v_readlane_b32 s6, v254, 31
	s_mov_b32 m0, s62
	v_readlane_b32 s7, v254, 32
	s_nop 4
	global_load_lds_dwordx4 v150, s[6:7]
	s_mov_b32 m0, s63
	s_nop 0
	global_load_lds_dwordx4 v148, s[6:7]
	s_cselect_b64 s[6:7], -1, 0
	s_cmp_lg_u32 s9, 1
	s_cbranch_scc1 .LBB0_857
	s_barrier

; #define PG8_STAGE(bufoff, gbase, voff) do { _Pragma("unroll") for (int _i = 0; _i < 2; ++_i) \
;         __builtin_amdgcn_global_load_lds((const unsigned*)((const char*)(gbase) + (voff)[_i]), (PG8_LAS unsigned*)(lds + (bufoff) + ldsw + _i * 8192), 16, 0, 0); } while (0)
; #define PG8_BAR __builtin_amdgcn_s_barrier()
; template <class Epi, class Sched, bool ALIGN_EPI = false, bool SP2 = false>
; __device__ __forceinline__ void gemm_phase(PG8_LAS unsigned char* lds, const Gemm g, const Sched& S, const Epi& E) {
;     ...
;     for (int i = 0; i < 2; ++i) { int R, C; stage_rc(tid * 16 + i * 8192, R, C); const int Rb = Epi::PERM ? ((R & ~31) + perm32(R & 31)) : R;
;         voffA[i] = (unsigned)(R * K + C) * 2u; voffB[i] = (unsigned)(Rb * K + C) * 2u; }
;     const size_t kstep = (size_t)(BK * 2);
;     const size_t hstep = (size_t)HALF * K * 2;
;     const size_t tstep = 2 * hstep;
;     const unsigned ldsw = (unsigned)wid * 1024u;
;     const int aoff = lds_byte(wr * 64 + fr, fq * 8), boff = lds_byte(wc * 32 + fr, fq * 8);
;     ...
;     Unit cur, nxt; int ui = 0;
;     if (!S.next(0, cur)) return;
;     f32x4 acc[2][2][4][2];
; #pragma unroll
;     for (int a = 0; a < 2; ++a)
; #pragma unroll
;         for (int b = 0; b < 2; ++b)
; #pragma unroll
;             for (int m = 0; m < 4; ++m)
; #pragma unroll
;                 for (int n = 0; n < 2; ++n) acc[a][b][m][n] = (f32x4){0.f, 0.f, 0.f, 0.f};
;     bf16x8 At[4][2], B0[2][2], B1[2][2];
;     const char* cA = (const char*)g.A + (size_t)cur.pm * tstep; const char* cB = (const char*)g.Bt + (size_t)cur.pn * tstep;
;     S.a_ready(cur);
;     if constexpr (SP2) {
;         PG8_STAGE(PG8_SB(0, 0), cB, voffB); PG8_STAGE(PG8_SB(0, 1), cB + hstep, voffB); PG8_STAGE(PG8_SA(0, 0), cA, voffA); PG8_STAGE(PG8_SA(0, 1), cA + hstep, voffA);
;         if (wr == 1) PG8_BAR;
;         PG8_WAIT_V(2); PG8_BAR;
;         PG8_STAGE(PG8_SB(1, 0), cB + kstep, voffB); PG8_STAGE(PG8_SA(1, 0), cA + kstep, voffA); PG8_STAGE(PG8_SB(1, 1), cB + hstep + kstep, voffB);
;         PG8_WAIT_V(6); PG8_BAR;
; __global__ void __launch_bounds__(512, 2) mk_fwd(Args a) {
;     ...
;         { pg8::Gemm g{H, Wl + W_DN, NTOK_P, DM, FF}; pg8::StaticOrder S; S.init(NTOK_P, DM, G, bx);
;           EpiRes E{xb2, l == 0 ? bufA : nullptr, l == 0 ? nullptr : a.out, l == 0 ? ss1n : nullptr};
;           pg8::gemm_phase<EpiRes, pg8::StaticOrder, true, true>(lds, g, S, E);
.LBB0_929:
	s_or_b64 exec, exec, s[0:1]
	s_add_u32 s14, s38, 0x21000
	v_readlane_b32 s0, v255, 25
	s_addc_u32 s15, s39, 0
	v_readlane_b32 s1, v255, 26
	s_and_b64 s[0:1], s[0:1], exec
	v_readlane_b32 s0, v255, 39
	v_mov_b32_e32 v24, v184
	v_readlane_b32 s1, v255, 40
	s_waitcnt lgkmcnt(0)
	s_cselect_b32 s17, 0, s69
	s_cselect_b32 s16, 0, s68
	s_and_b64 vcc, exec, s[0:1]
	v_readfirstlane_b32 s4, v24
	s_cbranch_vccz .Lbsh_g6_go
	s_barrier
	s_branch .LBB0_1029
.Lbsh_g6_go:
	v_lshlrev_b32_e32 v0, 4, v24
	v_add_u32_e32 v2, 0x2000, v0
	v_ashrrev_i32_e32 v3, 31, v2
	v_lshrrev_b32_e32 v3, 22, v3
	v_add_u32_e32 v3, v2, v3
	v_ashrrev_i32_e32 v25, 10, v3
	v_mul_i32_i24_e32 v3, 0x400, v25
	v_sub_u32_e32 v2, v2, v3
	v_lshrrev_b32_e32 v3, 4, v2
	v_bitop3_b32 v2, v3, v2, 32 bitop3:0x6c
	v_ashrrev_i32_e32 v3, 31, v2
	v_lshrrev_b32_e32 v3, 26, v3
	v_add_u32_e32 v3, v2, v3
	v_lshlrev_b32_e32 v20, 3, v25
	v_readlane_b32 s0, v255, 37
	v_ashrrev_i32_e32 v26, 6, v3
	v_and_b32_e32 v20, -16, v20
	s_add_u32 s26, s0, 0x1300000
	v_readlane_b32 s0, v255, 38
	v_add_u32_e32 v20, v26, v20
	s_addc_u32 s66, s0, 0
	v_and_b32_e32 v21, 3, v26
	s_mov_b32 s0, 0x7ffe0
	v_lshrrev_b32_e32 v22, 2, v20
	v_lshlrev_b32_e32 v23, 1, v20
	v_and_b32_e32 v3, 0xc0, v3
	v_and_or_b32 v21, v20, s0, v21
	v_and_b32_e32 v22, 4, v22
	v_and_b32_e32 v23, 24, v23
	v_sub_u32_e32 v2, v2, v3
	v_mov_b32_e32 v30, 1
	v_or3_b32 v21, v21, v22, v23
	v_lshlrev_b32_e32 v22, 5, v25
	v_ashrrev_i16_sdwa v2, v30, sext(v2) dst_sel:DWORD dst_unused:UNUSED_PAD src0_sel:DWORD src1_sel:BYTE_0
	v_and_b32_e32 v22, 32, v22
	v_bfe_i32 v27, v2, 0, 16
	v_add_lshl_u32 v3, v22, v27, 1
	v_lshl_add_u32 v2, v21, 13, v3
	v_lshl_add_u32 v176, v20, 13, v3
	v_bfe_i32 v3, v24, 27, 1
	v_lshrrev_b32_e32 v3, 22, v3
	v_add_u32_e32 v3, v0, v3
	v_and_b32_e32 v3, 0xfffffc00, v3
	v_sub_u32_e32 v0, v0, v3
	v_lshrrev_b32_e32 v3, 4, v0
	v_ashrrev_i32_e32 v20, 31, v24
	v_bitop3_b32 v0, v3, v0, 32 bitop3:0x6c
	v_lshrrev_b32_e32 v20, 26, v20
	v_ashrrev_i32_e32 v3, 31, v0
	v_add_u32_e32 v20, v24, v20
	v_lshrrev_b32_e32 v3, 26, v3
	v_ashrrev_i32_e32 v29, 6, v20
	v_add_u32_e32 v3, v0, v3
	v_lshlrev_b32_e32 v20, 3, v29
	v_ashrrev_i32_e32 v28, 6, v3
	v_and_b32_e32 v20, -16, v20
	v_add_u32_e32 v20, v28, v20
	v_and_b32_e32 v21, 3, v28
	v_lshrrev_b32_e32 v22, 2, v20
	v_lshlrev_b32_e32 v23, 1, v20
	v_and_b32_e32 v3, 0xc0, v3
	s_ashr_i32 s6, s4, 6
	v_and_or_b32 v21, v20, s0, v21
	v_and_b32_e32 v22, 4, v22
	v_and_b32_e32 v23, 24, v23
	v_sub_u32_e32 v0, v0, v3
	s_ashr_i32 s5, s4, 8
	s_lshl_b32 s67, s6, 10
	v_or3_b32 v21, v21, v22, v23
	v_lshlrev_b32_e32 v22, 5, v29
	v_ashrrev_i16_sdwa v0, v30, sext(v0) dst_sel:DWORD dst_unused:UNUSED_PAD src0_sel:DWORD src1_sel:BYTE_0
	v_readlane_b32 s0, v254, 47
	v_and_b32_e32 v22, 32, v22
	v_bfe_i32 v30, v0, 0, 16
	v_readlane_b32 s1, v254, 48
	s_add_u32 s0, s26, s0
	v_add_lshl_u32 v3, v22, v30, 1
	s_addc_u32 s1, s66, s1
	s_add_i32 s72, s67, 0
	v_lshl_add_u32 v0, v21, 13, v3
	s_add_i32 m0, s72, 0x10000
	v_lshl_add_u32 v178, v20, 13, v3
	global_load_lds_dwordx4 v0, s[0:1]
	s_add_i32 m0, s72, 0x12000
	s_add_u32 s8, s0, 0x100000
	global_load_lds_dwordx4 v2, s[0:1]
	s_addc_u32 s9, s1, 0
	s_add_i32 m0, s72, 0x14000
	s_add_i32 s73, s72, 0x2000
	global_load_lds_dwordx4 v0, s[8:9]
	s_add_i32 m0, s72, 0x16000
	s_add_i32 s74, s72, 0x4000
	global_load_lds_dwordx4 v2, s[8:9]
	v_readlane_b32 s8, v254, 51
	s_barrier
	s_mov_b32 m0, s72
	v_readlane_b32 s9, v254, 52
	s_add_i32 s75, s72, 0x6000
	v_mov_b32_e32 v3, v1
	s_cmp_eq_u32 s5, 1
	v_lshl_add_u64 v[20:21], s[0:1], 0, v[0:1]
	s_cselect_b64 s[18:19], -1, 0
	global_load_lds_dwordx4 v178, s[8:9]
	s_mov_b32 m0, s73
	s_cmp_lg_u32 s5, 1
	global_load_lds_dwordx4 v176, s[8:9]
	v_readlane_b32 s8, v254, 53
	s_mov_b32 m0, s74
	v_readlane_b32 s9, v254, 54
	v_lshl_add_u64 v[22:23], s[0:1], 0, v[2:3]
	s_nop 3
	global_load_lds_dwordx4 v178, s[8:9]
	s_mov_b32 m0, s75
	s_nop 0
	global_load_lds_dwordx4 v176, s[8:9]
	s_cbranch_scc1 .LBB0_932
	s_barrier
